# v28 + nt cache policy on the once-read f32 streams (prep x loads and all weight-convert loads), so they do not displace the bf16 residual/weights in L2/MALL
# baseline (speedup 1.0000x reference)
; DI void stb8(bf16_t* p, const F8& f) { *(uint4*)p = pack8(f); }
; DI void prep_phase(const Params& p) {
;     ...
;     for (size_t i = gt; i < (size_t)MT * 128; i += gn) {
;         const size_t e = i * 8;
;         const float* s = e < (size_t)MP * 1024 ? p.in[0] + e : p.in[1] + (e - (size_t)MP * 1024);
;         stb8(XB + e, ldf8(s));
;     }
.LBB0_8:
	v_lshl_add_u64 v[12:13], s[36:37], 0, v[6:7]
	v_lshl_add_u64 v[14:15], s[12:13], 0, v[6:7]
	v_cmp_gt_u64_e32 vcc, s[20:21], v[10:11]
	v_lshl_add_u64 v[10:11], v[10:11], 0, s[4:5]
	v_lshl_add_u64 v[6:7], v[6:7], 0, s[14:15]
	v_cndmask_b32_e32 v17, v15, v13, vcc
	v_cndmask_b32_e32 v16, v14, v12, vcc
	global_load_dwordx4 v[12:15], v[16:17], off nt
	s_nop 0
	global_load_dwordx4 v[16:19], v[16:17], off offset:16 nt
	v_cmp_lt_u64_e32 vcc, s[22:23], v[10:11]
	s_or_b64 s[18:19], vcc, s[18:19]
	s_waitcnt vmcnt(1)
	v_cvt_pk_bf16_f32 v12, v12, v13
	v_cvt_pk_bf16_f32 v13, v14, v15
	s_waitcnt vmcnt(0)
	v_cvt_pk_bf16_f32 v14, v16, v17
	v_cvt_pk_bf16_f32 v15, v18, v19
	global_store_dwordx4 v[8:9], v[12:15], off
	v_lshl_add_u64 v[8:9], v[8:9], 0, s[16:17]
	s_andn2_b64 exec, exec, s[18:19]
	s_cbranch_execnz .LBB0_8

; DI int bidx() { int b = blockIdx.x; asm volatile("" : "+s"(b)); return b; }
; DI int gdim() { int g = gridDim.x; asm volatile("" : "+s"(g)); return g; }
; DI void wconv(const float* __restrict__ src, bf16_t* __restrict__ dst, int K, int N, int Npad, int perm, unsigned char* smem) {
;     ...
;     for (int t = bidx(); t < T; t += gdim()) {
;         const int kt = t % nkt, ntile = t / nkt, k0 = kt * 64, n0 = ntile * 64;
; #pragma unroll
;         for (int j = 0; j < 2; ++j) {
;             const int k = (tid >> 4) + 32 * j, nl4 = (tid & 15) * 4, n = n0 + nl4;
;             float4 v = make_float4(0.f, 0.f, 0.f, 0.f);
;             if (n < N) v = *(const float4*)(src + (size_t)(k0 + k) * N + n);
;             float* tp = tile + k * 65 + nl4; tp[0] = v.x; tp[1] = v.y; tp[2] = v.z; tp[3] = v.w;
;         }
.LBB0_21:
	s_ashr_i32 s0, s6, 31
	s_lshr_b32 s0, s0, 28
	s_add_i32 s1, s6, s0
	s_and_b32 s0, s1, 0x3fffff0
	s_lshl_b32 s1, s1, 2
	s_andn2_b32 s1, s1, 63
	s_sub_i32 s0, s6, s0
	v_or_b32_e32 v12, s1, v14
	s_lshl_b32 s0, s0, 6
	v_cmp_gt_i32_e32 vcc, s7, v12
	v_mov_b32_e32 v2, 0
	v_mov_b32_e32 v3, 0
	v_mov_b32_e32 v4, 0
	v_mov_b32_e32 v5, 0
	v_mov_b32_e32 v6, 0
	v_mov_b32_e32 v7, 0
	v_mov_b32_e32 v8, 0
	v_mov_b32_e32 v9, 0
	s_and_saveexec_b64 s[4:5], vcc
	s_cbranch_execz .LBB0_23
	v_readlane_b32 s64, v252, 11
	v_ashrrev_i32_e32 v13, 31, v12
	v_readlane_b32 s65, v252, 12
	v_add_u32_e32 v6, s0, v1
	v_readlane_b32 s66, v252, 13
	v_lshl_add_u64 v[2:3], v[12:13], 2, s[64:65]
	v_mad_i64_i32 v[4:5], s[10:11], v6, s8, v[2:3]
	v_add_u32_e32 v6, 32, v6
	v_mad_i64_i32 v[6:7], s[10:11], v6, s8, v[2:3]
	global_load_dwordx4 v[2:5], v[4:5], off nt
	s_nop 0
	global_load_dwordx4 v[6:9], v[6:7], off nt
	v_readlane_b32 s67, v252, 14
	v_readlane_b32 s68, v252, 15
	v_readlane_b32 s69, v252, 16
	v_readlane_b32 s70, v252, 17
	v_readlane_b32 s71, v252, 18
	v_readlane_b32 s72, v252, 19
	v_readlane_b32 s73, v252, 20
	v_readlane_b32 s74, v252, 21
	v_readlane_b32 s75, v252, 22
	v_readlane_b32 s76, v252, 23
	v_readlane_b32 s77, v252, 24
	v_readlane_b32 s78, v252, 25
	v_readlane_b32 s79, v252, 26

; DI int bidx() { int b = blockIdx.x; asm volatile("" : "+s"(b)); return b; }
; DI int gdim() { int g = gridDim.x; asm volatile("" : "+s"(g)); return g; }
; DI void wconv(const float* __restrict__ src, bf16_t* __restrict__ dst, int K, int N, int Npad, int perm, unsigned char* smem) {
;     ...
;     for (int t = bidx(); t < T; t += gdim()) {
;         const int kt = t % nkt, ntile = t / nkt, k0 = kt * 64, n0 = ntile * 64;
; #pragma unroll
;         for (int j = 0; j < 2; ++j) {
;             const int k = (tid >> 4) + 32 * j, nl4 = (tid & 15) * 4, n = n0 + nl4;
;             float4 v = make_float4(0.f, 0.f, 0.f, 0.f);
;             if (n < N) v = *(const float4*)(src + (size_t)(k0 + k) * N + n);
;             float* tp = tile + k * 65 + nl4; tp[0] = v.x; tp[1] = v.y; tp[2] = v.z; tp[3] = v.w;
;         }
.LBB0_28:
	s_mul_hi_i32 s0, s6, 0x2aaaaaab
	s_lshr_b32 s1, s0, 31
	s_add_i32 s1, s0, s1
	s_mul_i32 s0, s1, 6
	s_lshl_b32 s1, s1, 6
	s_sub_i32 s0, s6, s0
	v_or_b32_e32 v12, s1, v14
	s_lshl_b32 s0, s0, 6
	v_cmp_gt_i32_e32 vcc, s7, v12
	v_mov_b32_e32 v2, 0
	v_mov_b32_e32 v3, 0
	v_mov_b32_e32 v4, 0
	v_mov_b32_e32 v5, 0
	v_mov_b32_e32 v6, 0
	v_mov_b32_e32 v7, 0
	v_mov_b32_e32 v8, 0
	v_mov_b32_e32 v9, 0
	s_and_saveexec_b64 s[4:5], vcc
	s_cbranch_execz .LBB0_30
	v_readlane_b32 s64, v252, 11
	v_ashrrev_i32_e32 v13, 31, v12
	v_readlane_b32 s70, v252, 17
	v_readlane_b32 s71, v252, 18
	v_add_u32_e32 v6, s0, v1
	v_readlane_b32 s65, v252, 12
	v_lshl_add_u64 v[2:3], v[12:13], 2, s[70:71]
	v_mad_i64_i32 v[4:5], s[10:11], v6, s8, v[2:3]
	v_add_u32_e32 v6, 32, v6
	v_mad_i64_i32 v[6:7], s[10:11], v6, s8, v[2:3]
	global_load_dwordx4 v[2:5], v[4:5], off nt
	s_nop 0
	global_load_dwordx4 v[6:9], v[6:7], off nt
	v_readlane_b32 s66, v252, 13
	v_readlane_b32 s67, v252, 14
	v_readlane_b32 s68, v252, 15
	v_readlane_b32 s69, v252, 16
	v_readlane_b32 s72, v252, 19
	v_readlane_b32 s73, v252, 20
	v_readlane_b32 s74, v252, 21
	v_readlane_b32 s75, v252, 22
	v_readlane_b32 s76, v252, 23
	v_readlane_b32 s77, v252, 24
	v_readlane_b32 s78, v252, 25
	v_readlane_b32 s79, v252, 26

; DI int bidx() { int b = blockIdx.x; asm volatile("" : "+s"(b)); return b; }
; DI int gdim() { int g = gridDim.x; asm volatile("" : "+s"(g)); return g; }
; DI void wconv(const float* __restrict__ src, bf16_t* __restrict__ dst, int K, int N, int Npad, int perm, unsigned char* smem) {
;     ...
;     for (int t = bidx(); t < T; t += gdim()) {
;         const int kt = t % nkt, ntile = t / nkt, k0 = kt * 64, n0 = ntile * 64;
; #pragma unroll
;         for (int j = 0; j < 2; ++j) {
;             const int k = (tid >> 4) + 32 * j, nl4 = (tid & 15) * 4, n = n0 + nl4;
;             float4 v = make_float4(0.f, 0.f, 0.f, 0.f);
;             if (n < N) v = *(const float4*)(src + (size_t)(k0 + k) * N + n);
;             float* tp = tile + k * 65 + nl4; tp[0] = v.x; tp[1] = v.y; tp[2] = v.z; tp[3] = v.w;
;         }
.LBB0_35:
	s_ashr_i32 s0, s6, 31
	s_lshr_b32 s0, s0, 30
	s_add_i32 s1, s6, s0
	s_and_b32 s0, s1, 0x3fffffc
	s_lshl_b32 s1, s1, 4
	s_andn2_b32 s1, s1, 63
	s_sub_i32 s0, s6, s0
	v_or_b32_e32 v12, s1, v14
	s_lshl_b32 s0, s0, 6
	v_cmp_gt_i32_e32 vcc, s7, v12
	v_mov_b32_e32 v2, 0
	v_mov_b32_e32 v3, 0
	v_mov_b32_e32 v4, 0
	v_mov_b32_e32 v5, 0
	v_mov_b32_e32 v6, 0
	v_mov_b32_e32 v7, 0
	v_mov_b32_e32 v8, 0
	v_mov_b32_e32 v9, 0
	s_and_saveexec_b64 s[4:5], vcc
	s_cbranch_execz .LBB0_37
	v_add_u32_e32 v4, s0, v1
	v_ashrrev_i32_e32 v5, 31, v4
	v_readlane_b32 s8, v252, 11
	v_lshlrev_b64 v[6:7], 12, v[4:5]
	v_add_u32_e32 v4, 32, v4
	v_ashrrev_i32_e32 v13, 31, v12
	v_readlane_b32 s16, v252, 19
	v_readlane_b32 s17, v252, 20
	v_ashrrev_i32_e32 v5, 31, v4
	v_lshlrev_b64 v[4:5], 12, v[4:5]
	v_lshl_add_u64 v[2:3], v[12:13], 2, s[16:17]
	v_lshl_add_u64 v[6:7], v[2:3], 0, v[6:7]
	v_lshl_add_u64 v[8:9], v[2:3], 0, v[4:5]
	global_load_dwordx4 v[2:5], v[6:7], off nt
	s_nop 0
	global_load_dwordx4 v[6:9], v[8:9], off nt
	v_readlane_b32 s9, v252, 12
	v_readlane_b32 s10, v252, 13
	v_readlane_b32 s11, v252, 14
	v_readlane_b32 s12, v252, 15
	v_readlane_b32 s13, v252, 16
	v_readlane_b32 s14, v252, 17
	v_readlane_b32 s15, v252, 18
	v_readlane_b32 s18, v252, 21
	v_readlane_b32 s19, v252, 22
	v_readlane_b32 s20, v252, 23
	v_readlane_b32 s21, v252, 24
	v_readlane_b32 s22, v252, 25
	v_readlane_b32 s23, v252, 26

; DI int bidx() { int b = blockIdx.x; asm volatile("" : "+s"(b)); return b; }
; DI int gdim() { int g = gridDim.x; asm volatile("" : "+s"(g)); return g; }
; DI void wconv(const float* __restrict__ src, bf16_t* __restrict__ dst, int K, int N, int Npad, int perm, unsigned char* smem) {
;     ...
;     for (int t = bidx(); t < T; t += gdim()) {
;         const int kt = t % nkt, ntile = t / nkt, k0 = kt * 64, n0 = ntile * 64;
; #pragma unroll
;         for (int j = 0; j < 2; ++j) {
;             const int k = (tid >> 4) + 32 * j, nl4 = (tid & 15) * 4, n = n0 + nl4;
;             float4 v = make_float4(0.f, 0.f, 0.f, 0.f);
;             if (n < N) v = *(const float4*)(src + (size_t)(k0 + k) * N + n);
;             float* tp = tile + k * 65 + nl4; tp[0] = v.x; tp[1] = v.y; tp[2] = v.z; tp[3] = v.w;
;         }
.LBB0_42:
	s_ashr_i32 s0, s6, 31
	s_lshr_b32 s0, s0, 28
	s_add_i32 s1, s6, s0
	s_and_b32 s0, s1, 0x3fffff0
	s_lshl_b32 s1, s1, 2
	s_andn2_b32 s1, s1, 63
	s_sub_i32 s0, s6, s0
	v_or_b32_e32 v12, s1, v14
	s_lshl_b32 s0, s0, 6
	v_cmp_gt_i32_e32 vcc, s7, v12
	v_mov_b32_e32 v2, 0
	v_mov_b32_e32 v3, 0
	v_mov_b32_e32 v4, 0
	v_mov_b32_e32 v5, 0
	v_mov_b32_e32 v6, 0
	v_mov_b32_e32 v7, 0
	v_mov_b32_e32 v8, 0
	v_mov_b32_e32 v9, 0
	s_and_saveexec_b64 s[4:5], vcc
	s_cbranch_execz .LBB0_44
	v_add_u32_e32 v4, s0, v1
	v_ashrrev_i32_e32 v5, 31, v4
	v_readlane_b32 s8, v252, 11
	v_lshlrev_b64 v[6:7], 12, v[4:5]
	v_add_u32_e32 v4, 32, v4
	v_ashrrev_i32_e32 v13, 31, v12
	v_readlane_b32 s20, v252, 23
	v_readlane_b32 s21, v252, 24
	v_ashrrev_i32_e32 v5, 31, v4
	v_lshlrev_b64 v[4:5], 12, v[4:5]
	v_lshl_add_u64 v[2:3], v[12:13], 2, s[20:21]
	v_lshl_add_u64 v[6:7], v[2:3], 0, v[6:7]
	v_lshl_add_u64 v[8:9], v[2:3], 0, v[4:5]
	global_load_dwordx4 v[2:5], v[6:7], off nt
	s_nop 0
	global_load_dwordx4 v[6:9], v[8:9], off nt
	v_readlane_b32 s9, v252, 12
	v_readlane_b32 s10, v252, 13
	v_readlane_b32 s11, v252, 14
	v_readlane_b32 s12, v252, 15
	v_readlane_b32 s13, v252, 16
	v_readlane_b32 s14, v252, 17
	v_readlane_b32 s15, v252, 18
	v_readlane_b32 s16, v252, 19
	v_readlane_b32 s17, v252, 20
	v_readlane_b32 s18, v252, 21
	v_readlane_b32 s19, v252, 22
	v_readlane_b32 s22, v252, 25
	v_readlane_b32 s23, v252, 26

; DI int bidx() { int b = blockIdx.x; asm volatile("" : "+s"(b)); return b; }
; DI int gdim() { int g = gridDim.x; asm volatile("" : "+s"(g)); return g; }
; DI void wconv(const float* __restrict__ src, bf16_t* __restrict__ dst, int K, int N, int Npad, int perm, unsigned char* smem) {
;     ...
;     for (int t = bidx(); t < T; t += gdim()) {
;         const int kt = t % nkt, ntile = t / nkt, k0 = kt * 64, n0 = ntile * 64;
; #pragma unroll
;         for (int j = 0; j < 2; ++j) {
;             const int k = (tid >> 4) + 32 * j, nl4 = (tid & 15) * 4, n = n0 + nl4;
;             float4 v = make_float4(0.f, 0.f, 0.f, 0.f);
;             if (n < N) v = *(const float4*)(src + (size_t)(k0 + k) * N + n);
;             float* tp = tile + k * 65 + nl4; tp[0] = v.x; tp[1] = v.y; tp[2] = v.z; tp[3] = v.w;
;         }
.LBB0_50:
	s_ashr_i32 s0, s8, 31
	s_lshr_b32 s0, s0, 28
	s_add_i32 s1, s8, s0
	s_and_b32 s0, s1, 0x3fffff0
	s_lshl_b32 s1, s1, 2
	s_andn2_b32 s1, s1, 63
	s_sub_i32 s0, s8, s0
	v_or_b32_e32 v12, s1, v14
	s_lshl_b32 s0, s0, 6
	v_cmp_gt_i32_e32 vcc, s9, v12
	v_mov_b32_e32 v2, 0
	v_mov_b32_e32 v3, 0
	v_mov_b32_e32 v4, 0
	v_mov_b32_e32 v5, 0
	v_mov_b32_e32 v6, 0
	v_mov_b32_e32 v7, 0
	v_mov_b32_e32 v8, 0
	v_mov_b32_e32 v9, 0
	s_and_saveexec_b64 s[4:5], vcc
	s_cbranch_execz .LBB0_52
	v_readlane_b32 s64, v252, 27
	v_ashrrev_i32_e32 v13, 31, v12
	v_readlane_b32 s74, v252, 37
	v_readlane_b32 s75, v252, 38
	v_add_u32_e32 v6, s0, v1
	v_readlane_b32 s65, v252, 28
	v_lshl_add_u64 v[2:3], v[12:13], 2, s[74:75]
	v_mad_i64_i32 v[4:5], s[6:7], v6, s10, v[2:3]
	v_add_u32_e32 v6, 32, v6
	v_mad_i64_i32 v[6:7], s[6:7], v6, s10, v[2:3]
	global_load_dwordx4 v[2:5], v[4:5], off nt
	s_nop 0
	global_load_dwordx4 v[6:9], v[6:7], off nt
	v_readlane_b32 s66, v252, 29
	v_readlane_b32 s67, v252, 30
	v_readlane_b32 s68, v252, 31
	v_readlane_b32 s69, v252, 32
	v_readlane_b32 s70, v252, 33
	v_readlane_b32 s71, v252, 34
	v_readlane_b32 s72, v252, 35
	v_readlane_b32 s73, v252, 36
	v_readlane_b32 s76, v252, 39
	v_readlane_b32 s77, v252, 40
	v_readlane_b32 s78, v252, 41
	v_readlane_b32 s79, v252, 42

; DI int bidx() { int b = blockIdx.x; asm volatile("" : "+s"(b)); return b; }
; DI int gdim() { int g = gridDim.x; asm volatile("" : "+s"(g)); return g; }
; DI void wconv(const float* __restrict__ src, bf16_t* __restrict__ dst, int K, int N, int Npad, int perm, unsigned char* smem) {
;     ...
;     for (int t = bidx(); t < T; t += gdim()) {
;         const int kt = t % nkt, ntile = t / nkt, k0 = kt * 64, n0 = ntile * 64;
; #pragma unroll
;         for (int j = 0; j < 2; ++j) {
;             const int k = (tid >> 4) + 32 * j, nl4 = (tid & 15) * 4, n = n0 + nl4;
;             float4 v = make_float4(0.f, 0.f, 0.f, 0.f);
;             if (n < N) v = *(const float4*)(src + (size_t)(k0 + k) * N + n);
;             float* tp = tile + k * 65 + nl4; tp[0] = v.x; tp[1] = v.y; tp[2] = v.z; tp[3] = v.w;
;         }
.LBB0_60:
	s_mul_hi_i32 s0, s6, 0x2e8ba2e9
	s_lshr_b32 s1, s0, 31
	s_ashr_i32 s0, s0, 3
	s_add_i32 s1, s0, s1
	s_mul_i32 s0, s1, 44
	s_lshl_b32 s1, s1, 6
	s_sub_i32 s0, s6, s0
	v_or_b32_e32 v12, s1, v14
	s_lshl_b32 s0, s0, 6
	v_cmp_gt_i32_e32 vcc, s7, v12
	v_mov_b32_e32 v2, 0
	v_mov_b32_e32 v3, 0
	v_mov_b32_e32 v4, 0
	v_mov_b32_e32 v5, 0
	v_mov_b32_e32 v6, 0
	v_mov_b32_e32 v7, 0
	v_mov_b32_e32 v8, 0
	v_mov_b32_e32 v9, 0
	s_and_saveexec_b64 s[4:5], vcc
	s_cbranch_execz .LBB0_62
	v_add_u32_e32 v4, s0, v1
	v_ashrrev_i32_e32 v5, 31, v4
	v_readlane_b32 s64, v252, 27
	v_lshlrev_b64 v[6:7], 12, v[4:5]
	v_add_u32_e32 v4, 32, v4
	v_ashrrev_i32_e32 v13, 31, v12
	v_readlane_b32 s78, v252, 41
	v_readlane_b32 s79, v252, 42
	v_ashrrev_i32_e32 v5, 31, v4
	v_lshlrev_b64 v[4:5], 12, v[4:5]
	v_lshl_add_u64 v[2:3], v[12:13], 2, s[78:79]
	v_lshl_add_u64 v[6:7], v[2:3], 0, v[6:7]
	v_lshl_add_u64 v[8:9], v[2:3], 0, v[4:5]
	global_load_dwordx4 v[2:5], v[6:7], off nt
	s_nop 0
	global_load_dwordx4 v[6:9], v[8:9], off nt
	v_readlane_b32 s65, v252, 28
	v_readlane_b32 s66, v252, 29
	v_readlane_b32 s67, v252, 30
	v_readlane_b32 s68, v252, 31
	v_readlane_b32 s69, v252, 32
	v_readlane_b32 s70, v252, 33
	v_readlane_b32 s71, v252, 34
	v_readlane_b32 s72, v252, 35
	v_readlane_b32 s73, v252, 36
	v_readlane_b32 s74, v252, 37
	v_readlane_b32 s75, v252, 38
	v_readlane_b32 s76, v252, 39
	v_readlane_b32 s77, v252, 40

; DI int bidx() { int b = blockIdx.x; asm volatile("" : "+s"(b)); return b; }
; DI int gdim() { int g = gridDim.x; asm volatile("" : "+s"(g)); return g; }
; DI void wconv(const float* __restrict__ src, bf16_t* __restrict__ dst, int K, int N, int Npad, int perm, unsigned char* smem) {
;     ...
;     for (int t = bidx(); t < T; t += gdim()) {
;         const int kt = t % nkt, ntile = t / nkt, k0 = kt * 64, n0 = ntile * 64;
; #pragma unroll
;         for (int j = 0; j < 2; ++j) {
;             const int k = (tid >> 4) + 32 * j, nl4 = (tid & 15) * 4, n = n0 + nl4;
;             float4 v = make_float4(0.f, 0.f, 0.f, 0.f);
;             if (n < N) v = *(const float4*)(src + (size_t)(k0 + k) * N + n);
;             float* tp = tile + k * 65 + nl4; tp[0] = v.x; tp[1] = v.y; tp[2] = v.z; tp[3] = v.w;
;         }
.LBB0_1537:
	s_ashr_i32 s6, s18, 31
	s_lshr_b32 s6, s6, 28
	s_add_i32 s7, s18, s6
	s_and_b32 s6, s7, 0x3fffff0
	s_lshl_b32 s7, s7, 2
	s_andn2_b32 s7, s7, 63
	s_sub_i32 s6, s18, s6
	v_or_b32_e32 v8, s7, v11
	s_movk_i32 s14, 0x8a0
	s_lshl_b32 s6, s6, 6
	v_cmp_gt_i32_e32 vcc, s14, v8
	v_mov_b32_e32 v0, 0
	v_mov_b32_e32 v1, 0
	v_mov_b32_e32 v2, 0
	v_mov_b32_e32 v3, 0
	v_mov_b32_e32 v4, 0
	v_mov_b32_e32 v5, 0
	v_mov_b32_e32 v6, 0
	v_mov_b32_e32 v7, 0
	s_and_saveexec_b64 s[14:15], vcc
	s_cbranch_execz .LBB0_1539
	v_ashrrev_i32_e32 v9, 31, v8
	v_lshl_add_u64 v[0:1], v[8:9], 2, s[0:1]
	v_add_u32_e32 v4, s6, v10
	s_movk_i32 s19, 0x2280
	v_mad_i64_i32 v[2:3], s[26:27], v4, s19, v[0:1]
	v_add_u32_e32 v4, 32, v4
	v_mad_i64_i32 v[4:5], s[26:27], v4, s19, v[0:1]
	global_load_dwordx4 v[0:3], v[2:3], off nt
	s_nop 0
	global_load_dwordx4 v[4:7], v[4:5], off nt

; DI int bidx() { int b = blockIdx.x; asm volatile("" : "+s"(b)); return b; }
; DI int gdim() { int g = gridDim.x; asm volatile("" : "+s"(g)); return g; }
; DI void wconv(const float* __restrict__ src, bf16_t* __restrict__ dst, int K, int N, int Npad, int perm, unsigned char* smem) {
;     ...
;     for (int t = bidx(); t < T; t += gdim()) {
;         const int kt = t % nkt, ntile = t / nkt, k0 = kt * 64, n0 = ntile * 64;
; #pragma unroll
;         for (int j = 0; j < 2; ++j) {
;             const int k = (tid >> 4) + 32 * j, nl4 = (tid & 15) * 4, n = n0 + nl4;
;             float4 v = make_float4(0.f, 0.f, 0.f, 0.f);
;             if (n < N) v = *(const float4*)(src + (size_t)(k0 + k) * N + n);
;             float* tp = tile + k * 65 + nl4; tp[0] = v.x; tp[1] = v.y; tp[2] = v.z; tp[3] = v.w;
;         }
.LBB0_1544:
	s_mul_hi_i32 s6, s18, 0x2aaaaaab
	s_lshr_b32 s7, s6, 31
	s_add_i32 s7, s6, s7
	s_mul_i32 s6, s7, 6
	s_lshl_b32 s7, s7, 6
	s_sub_i32 s6, s18, s6
	v_or_b32_e32 v8, s7, v11
	s_lshl_b32 s6, s6, 6
	v_cmp_gt_i32_e32 vcc, s23, v8
	v_mov_b32_e32 v0, 0
	v_mov_b32_e32 v1, 0
	v_mov_b32_e32 v2, 0
	v_mov_b32_e32 v3, 0
	v_mov_b32_e32 v4, 0
	v_mov_b32_e32 v5, 0
	v_mov_b32_e32 v6, 0
	v_mov_b32_e32 v7, 0
	s_and_saveexec_b64 s[14:15], vcc
	s_cbranch_execz .LBB0_1546
	v_ashrrev_i32_e32 v9, 31, v8
	v_lshl_add_u64 v[0:1], v[8:9], 2, s[0:1]
	v_add_u32_e32 v4, s6, v10
	s_movk_i32 s19, 0xc00
	v_mad_i64_i32 v[2:3], s[26:27], v4, s19, v[0:1]
	v_add_u32_e32 v4, 32, v4
	v_mad_i64_i32 v[4:5], s[26:27], v4, s19, v[0:1]
	global_load_dwordx4 v[0:3], v[2:3], off nt
	s_nop 0
	global_load_dwordx4 v[4:7], v[4:5], off nt

; DI int bidx() { int b = blockIdx.x; asm volatile("" : "+s"(b)); return b; }
; DI int gdim() { int g = gridDim.x; asm volatile("" : "+s"(g)); return g; }
; DI void wconv(const float* __restrict__ src, bf16_t* __restrict__ dst, int K, int N, int Npad, int perm, unsigned char* smem) {
;     ...
;     for (int t = bidx(); t < T; t += gdim()) {
;         const int kt = t % nkt, ntile = t / nkt, k0 = kt * 64, n0 = ntile * 64;
; #pragma unroll
;         for (int j = 0; j < 2; ++j) {
;             const int k = (tid >> 4) + 32 * j, nl4 = (tid & 15) * 4, n = n0 + nl4;
;             float4 v = make_float4(0.f, 0.f, 0.f, 0.f);
;             if (n < N) v = *(const float4*)(src + (size_t)(k0 + k) * N + n);
;             float* tp = tile + k * 65 + nl4; tp[0] = v.x; tp[1] = v.y; tp[2] = v.z; tp[3] = v.w;
;         }
.LBB0_1552:
	s_ashr_i32 s6, s18, 31
	s_lshr_b32 s6, s6, 30
	s_add_i32 s7, s18, s6
	s_and_b32 s6, s7, 0x3fffffc
	s_lshl_b32 s7, s7, 4
	s_andn2_b32 s7, s7, 63
	s_sub_i32 s6, s18, s6
	v_or_b32_e32 v8, s7, v11
	s_lshl_b32 s6, s6, 6
	v_cmp_gt_i32_e32 vcc, s19, v8
	v_mov_b32_e32 v0, 0
	v_mov_b32_e32 v1, 0
	v_mov_b32_e32 v2, 0
	v_mov_b32_e32 v3, 0
	v_mov_b32_e32 v4, 0
	v_mov_b32_e32 v5, 0
	v_mov_b32_e32 v6, 0
	v_mov_b32_e32 v7, 0
	s_and_saveexec_b64 s[14:15], vcc
	s_cbranch_execz .LBB0_1554
	v_add_u32_e32 v2, s6, v10
	v_ashrrev_i32_e32 v3, 31, v2
	v_lshlrev_b64 v[4:5], 12, v[2:3]
	v_add_u32_e32 v2, 32, v2
	v_ashrrev_i32_e32 v9, 31, v8
	v_ashrrev_i32_e32 v3, 31, v2
	v_lshl_add_u64 v[0:1], v[8:9], 2, s[0:1]
	v_lshlrev_b64 v[2:3], 12, v[2:3]
	v_lshl_add_u64 v[4:5], v[0:1], 0, v[4:5]
	v_lshl_add_u64 v[6:7], v[0:1], 0, v[2:3]
	global_load_dwordx4 v[0:3], v[4:5], off nt
	s_nop 0
	global_load_dwordx4 v[4:7], v[6:7], off nt

; DI int bidx() { int b = blockIdx.x; asm volatile("" : "+s"(b)); return b; }
; DI int gdim() { int g = gridDim.x; asm volatile("" : "+s"(g)); return g; }
; DI void wconv(const float* __restrict__ src, bf16_t* __restrict__ dst, int K, int N, int Npad, int perm, unsigned char* smem) {
;     ...
;     for (int t = bidx(); t < T; t += gdim()) {
;         const int kt = t % nkt, ntile = t / nkt, k0 = kt * 64, n0 = ntile * 64;
; #pragma unroll
;         for (int j = 0; j < 2; ++j) {
;             const int k = (tid >> 4) + 32 * j, nl4 = (tid & 15) * 4, n = n0 + nl4;
;             float4 v = make_float4(0.f, 0.f, 0.f, 0.f);
;             if (n < N) v = *(const float4*)(src + (size_t)(k0 + k) * N + n);
;             float* tp = tile + k * 65 + nl4; tp[0] = v.x; tp[1] = v.y; tp[2] = v.z; tp[3] = v.w;
;         }
.LBB0_1560:
	s_ashr_i32 s6, s18, 31
	s_lshr_b32 s6, s6, 28
	s_add_i32 s7, s18, s6
	s_and_b32 s6, s7, 0x3fffff0
	s_lshl_b32 s7, s7, 2
	s_andn2_b32 s7, s7, 63
	s_sub_i32 s6, s18, s6
	v_or_b32_e32 v8, s7, v11
	s_movk_i32 s14, 0x400
	s_lshl_b32 s6, s6, 6
	v_cmp_gt_i32_e32 vcc, s14, v8
	v_mov_b32_e32 v0, 0
	v_mov_b32_e32 v1, 0
	v_mov_b32_e32 v2, 0
	v_mov_b32_e32 v3, 0
	v_mov_b32_e32 v4, 0
	v_mov_b32_e32 v5, 0
	v_mov_b32_e32 v6, 0
	v_mov_b32_e32 v7, 0
	s_and_saveexec_b64 s[14:15], vcc
	s_cbranch_execz .LBB0_1562
	v_add_u32_e32 v2, s6, v10
	v_ashrrev_i32_e32 v3, 31, v2
	v_lshlrev_b64 v[4:5], 12, v[2:3]
	v_add_u32_e32 v2, 32, v2
	v_ashrrev_i32_e32 v9, 31, v8
	v_ashrrev_i32_e32 v3, 31, v2
	v_lshl_add_u64 v[0:1], v[8:9], 2, s[0:1]
	v_lshlrev_b64 v[2:3], 12, v[2:3]
	v_lshl_add_u64 v[4:5], v[0:1], 0, v[4:5]
	v_lshl_add_u64 v[6:7], v[0:1], 0, v[2:3]
	global_load_dwordx4 v[0:3], v[4:5], off nt
	s_nop 0
	global_load_dwordx4 v[4:7], v[6:7], off nt

; DI int bidx() { int b = blockIdx.x; asm volatile("" : "+s"(b)); return b; }
; DI int gdim() { int g = gridDim.x; asm volatile("" : "+s"(g)); return g; }
; DI void wconv(const float* __restrict__ src, bf16_t* __restrict__ dst, int K, int N, int Npad, int perm, unsigned char* smem) {
;     ...
;     for (int t = bidx(); t < T; t += gdim()) {
;         const int kt = t % nkt, ntile = t / nkt, k0 = kt * 64, n0 = ntile * 64;
; #pragma unroll
;         for (int j = 0; j < 2; ++j) {
;             const int k = (tid >> 4) + 32 * j, nl4 = (tid & 15) * 4, n = n0 + nl4;
;             float4 v = make_float4(0.f, 0.f, 0.f, 0.f);
;             if (n < N) v = *(const float4*)(src + (size_t)(k0 + k) * N + n);
;             float* tp = tile + k * 65 + nl4; tp[0] = v.x; tp[1] = v.y; tp[2] = v.z; tp[3] = v.w;
;         }
.LBB0_1569:
	s_ashr_i32 s6, s18, 31
	s_lshr_b32 s6, s6, 28
	s_add_i32 s7, s18, s6
	s_and_b32 s6, s7, 0x3fffff0
	s_lshl_b32 s7, s7, 2
	s_andn2_b32 s7, s7, 63
	s_sub_i32 s6, s18, s6
	v_or_b32_e32 v8, s7, v11
	s_movk_i32 s14, 0x1010
	s_lshl_b32 s6, s6, 6
	v_cmp_gt_i32_e32 vcc, s14, v8
	v_mov_b32_e32 v0, 0
	v_mov_b32_e32 v1, 0
	v_mov_b32_e32 v2, 0
	v_mov_b32_e32 v3, 0
	v_mov_b32_e32 v4, 0
	v_mov_b32_e32 v5, 0
	v_mov_b32_e32 v6, 0
	v_mov_b32_e32 v7, 0
	s_and_saveexec_b64 s[14:15], vcc
	s_cbranch_execz .LBB0_1571
	v_ashrrev_i32_e32 v9, 31, v8
	v_lshl_add_u64 v[0:1], v[8:9], 2, s[0:1]
	v_add_u32_e32 v4, s6, v10
	s_movk_i32 s19, 0x4040
	v_mad_i64_i32 v[2:3], s[26:27], v4, s19, v[0:1]
	v_add_u32_e32 v4, 32, v4
	v_mad_i64_i32 v[4:5], s[26:27], v4, s19, v[0:1]
	global_load_dwordx4 v[0:3], v[2:3], off nt
	s_nop 0
	global_load_dwordx4 v[4:7], v[4:5], off nt

; DI int bidx() { int b = blockIdx.x; asm volatile("" : "+s"(b)); return b; }
; DI int gdim() { int g = gridDim.x; asm volatile("" : "+s"(g)); return g; }
; DI void wconv(const float* __restrict__ src, bf16_t* __restrict__ dst, int K, int N, int Npad, int perm, unsigned char* smem) {
;     ...
;     for (int t = bidx(); t < T; t += gdim()) {
;         const int kt = t % nkt, ntile = t / nkt, k0 = kt * 64, n0 = ntile * 64;
; #pragma unroll
;         for (int j = 0; j < 2; ++j) {
;             const int k = (tid >> 4) + 32 * j, nl4 = (tid & 15) * 4, n = n0 + nl4;
;             float4 v = make_float4(0.f, 0.f, 0.f, 0.f);
;             if (n < N) v = *(const float4*)(src + (size_t)(k0 + k) * N + n);
;             float* tp = tile + k * 65 + nl4; tp[0] = v.x; tp[1] = v.y; tp[2] = v.z; tp[3] = v.w;
;         }
.LBB0_1584:
	s_ashr_i32 s6, s23, 31
	s_lshr_b32 s6, s6, 28
	s_add_i32 s7, s23, s6
	s_and_b32 s6, s7, 0x3fffff0
	s_lshl_b32 s7, s7, 2
	s_andn2_b32 s7, s7, 63
	s_sub_i32 s6, s23, s6
	v_or_b32_e32 v8, s7, v11
	s_lshl_b32 s6, s6, 6
	v_cmp_gt_i32_e32 vcc, s31, v8
	v_mov_b32_e32 v0, 0
	v_mov_b32_e32 v1, 0
	v_mov_b32_e32 v2, 0
	v_mov_b32_e32 v3, 0
	v_mov_b32_e32 v4, 0
	v_mov_b32_e32 v5, 0
	v_mov_b32_e32 v6, 0
	v_mov_b32_e32 v7, 0
	s_and_saveexec_b64 s[14:15], vcc
	s_cbranch_execz .LBB0_1586
	v_ashrrev_i32_e32 v9, 31, v8
	v_lshl_add_u64 v[0:1], v[8:9], 2, s[0:1]
	v_add_u32_e32 v4, s6, v10
	v_mad_i64_i32 v[2:3], s[18:19], v4, s30, v[0:1]
	v_add_u32_e32 v4, 32, v4
	v_mad_i64_i32 v[4:5], s[18:19], v4, s30, v[0:1]
	global_load_dwordx4 v[0:3], v[2:3], off nt
	s_nop 0
	global_load_dwordx4 v[4:7], v[4:5], off nt

; DI int bidx() { int b = blockIdx.x; asm volatile("" : "+s"(b)); return b; }
; DI int gdim() { int g = gridDim.x; asm volatile("" : "+s"(g)); return g; }
; DI void wconv(const float* __restrict__ src, bf16_t* __restrict__ dst, int K, int N, int Npad, int perm, unsigned char* smem) {
;     ...
;     for (int t = bidx(); t < T; t += gdim()) {
;         const int kt = t % nkt, ntile = t / nkt, k0 = kt * 64, n0 = ntile * 64;
; #pragma unroll
;         for (int j = 0; j < 2; ++j) {
;             const int k = (tid >> 4) + 32 * j, nl4 = (tid & 15) * 4, n = n0 + nl4;
;             float4 v = make_float4(0.f, 0.f, 0.f, 0.f);
;             if (n < N) v = *(const float4*)(src + (size_t)(k0 + k) * N + n);
;             float* tp = tile + k * 65 + nl4; tp[0] = v.x; tp[1] = v.y; tp[2] = v.z; tp[3] = v.w;
;         }
.LBB0_1595:
	s_mul_hi_i32 s6, s18, 0x2e8ba2e9
	s_lshr_b32 s7, s6, 31
	s_ashr_i32 s6, s6, 3
	s_add_i32 s7, s6, s7
	s_mul_i32 s6, s7, 44
	s_lshl_b32 s7, s7, 6
	s_sub_i32 s6, s18, s6
	v_or_b32_e32 v8, s7, v11
	s_lshl_b32 s6, s6, 6
	v_cmp_gt_i32_e32 vcc, s19, v8
	v_mov_b32_e32 v0, 0
	v_mov_b32_e32 v1, 0
	v_mov_b32_e32 v2, 0
	v_mov_b32_e32 v3, 0
	v_mov_b32_e32 v4, 0
	v_mov_b32_e32 v5, 0
	v_mov_b32_e32 v6, 0
	v_mov_b32_e32 v7, 0
	s_and_saveexec_b64 s[14:15], vcc
	s_cbranch_execz .LBB0_1597
	v_add_u32_e32 v2, s6, v10
	v_ashrrev_i32_e32 v3, 31, v2
	v_lshlrev_b64 v[4:5], 12, v[2:3]
	v_add_u32_e32 v2, 32, v2
	v_ashrrev_i32_e32 v9, 31, v8
	v_ashrrev_i32_e32 v3, 31, v2
	v_lshl_add_u64 v[0:1], v[8:9], 2, s[0:1]
	v_lshlrev_b64 v[2:3], 12, v[2:3]
	v_lshl_add_u64 v[4:5], v[0:1], 0, v[4:5]
	v_lshl_add_u64 v[6:7], v[0:1], 0, v[2:3]
	global_load_dwordx4 v[0:3], v[4:5], off nt
	s_nop 0
	global_load_dwordx4 v[4:7], v[6:7], off nt
